# attention Q fragment loads (16-byte pieces at 32-byte stride) with the default cache policy instead of nt
# speedup vs baseline: 1.0030x; 1.0030x over previous
.LBB0_583:
	v_mov_b32_e32 v2, v252
	s_ashr_i32 s0, s2, 6
	v_readfirstlane_b32 s1, v2
	s_ashr_i32 s36, s1, 6
	s_and_b32 s1, s1, 0x3fffffc0
	s_lshl_b32 s1, s1, 2
	s_add_i32 s28, s1, 0
	s_ashr_i32 s1, s0, 31
	s_lshl_b64 s[4:5], s[0:1], 11
	s_lshl_b32 s1, s2, 8
	s_and_b32 s1, s1, 0x700
	s_or_b32 s1, s4, s1
	s_lshl_b32 s4, s36, 5
	s_bfe_u32 s10, s2, 0x30003
	s_add_i32 s28, s28, 0x18000
	s_ashr_i32 s6, s4, 31
	v_and_b32_e32 v148, 31, v2
	s_add_u32 s4, s1, s4
	v_or_b32_e32 v0, s4, v148
	s_movk_i32 s1, 0xc00
	s_addc_u32 s5, s5, s6
	v_mad_u64_u32 v[0:1], s[6:7], v0, s1, v[146:147]
	v_bfe_u32 v175, v2, 5, 1
	v_mad_i32_i24 v1, s5, v149, v1
	s_mul_i32 s16, s10, 0x180
	v_lshl_add_u64 v[0:1], v[0:1], 0, s[16:17]
	v_lshlrev_b32_e32 v144, 4, v175
	v_lshl_add_u64 v[0:1], v[0:1], 0, v[144:145]
	global_load_dwordx4 v[140:143], v[0:1], off
	global_load_dwordx4 v[136:139], v[0:1], off offset:32
	global_load_dwordx4 v[132:135], v[0:1], off offset:64
	global_load_dwordx4 v[128:131], v[0:1], off offset:96
	global_load_dwordx4 v[124:127], v[0:1], off offset:128
	global_load_dwordx4 v[120:123], v[0:1], off offset:160
	global_load_dwordx4 v[116:119], v[0:1], off offset:192
	global_load_dwordx4 v[112:115], v[0:1], off offset:224
	global_load_dwordx4 v[108:111], v[0:1], off offset:256
	global_load_dwordx4 v[104:107], v[0:1], off offset:288
	global_load_dwordx4 v[100:103], v[0:1], off offset:320
	global_load_dwordx4 v[96:99], v[0:1], off offset:352
	v_and_b32_e32 v52, 63, v2
	v_lshlrev_b32_e32 v10, 4, v2
	v_lshlrev_b32_e32 v0, 3, v52
	v_and_b32_e32 v1, 0xc0, v10
	v_lshlrev_b32_e32 v3, 1, v2
	s_lshl_b32 s1, s36, 3
	v_and_or_b32 v1, v0, 24, v1
	v_and_b32_e32 v3, 32, v3
	v_and_b32_e32 v0, 0x100, v0
	s_lshl_b32 s16, s10, 7
	s_and_b32 s6, s1, 0x3ffff0
	v_lshrrev_b32_e32 v4, 1, v2
	s_lshl_b32 s7, s36, 2
	v_or3_b32 v176, v1, v3, v0
	v_bfe_u32 v0, v2, 2, 2
	v_and_b32_e32 v4, 8, v4
	s_cmp_lg_u32 0, -1
	v_or3_b32 v0, v4, v0, s6
	s_cselect_b32 s6, 0, 0
	v_lshlrev_b32_e32 v53, 3, v2
	v_add_u32_e32 v179, s6, v176
	s_lshl_b32 s6, s0, 11
	v_bfe_u32 v1, v2, 4, 2
	v_and_or_b32 v0, s7, 4, v0
	v_and_b32_e32 v4, 24, v53
	s_ashr_i32 s7, s6, 31
	v_lshl_or_b32 v0, v0, 10, v4
	v_lshlrev_b32_e32 v4, 10, v1
	v_bitop3_b32 v5, v1, v2, 15 bitop3:0x78
	s_lshl_b64 s[10:11], s[6:7], 11
	v_lshl_or_b32 v4, s36, 13, v4
	v_lshlrev_b32_e32 v5, 3, v5
	s_add_u32 s12, s18, s10
	v_and_b32_e32 v3, 15, v2
	v_or3_b32 v150, v5, v4, s16
	v_and_b32_e32 v4, 32, v2
	v_or3_b32 v1, v1, s1, 4
	s_addc_u32 s13, s19, s11
	v_or3_b32 v0, v4, v0, s16
	v_lshlrev_b32_e32 v4, 10, v1
	v_bitop3_b32 v1, v1, v3, 7 bitop3:0x6c
	s_add_u32 s10, s20, s10
	v_lshlrev_b32_e32 v1, 3, v1
	s_addc_u32 s11, s21, s11
	s_lshl_b64 s[30:31], s[6:7], 7
	v_or3_b32 v152, v1, v4, s16
	v_bfe_u32 v1, v2, 3, 3
	s_add_u32 s34, s52, s30
	v_or_b32_e32 v1, s1, v1
	s_addc_u32 s35, s53, s31
	s_lshl_b32 s1, s36, 11
	v_lshlrev_b32_e32 v3, 6, v1
	v_lshrrev_b32_e32 v1, 1, v1
	v_ashrrev_i32_e32 v151, 31, v150
	s_add_i32 s29, s1, 0
	v_xor_b32_e32 v1, v1, v2
	v_lshlrev_b64 v[4:5], 1, v[150:151]
	s_add_i32 s30, s29, 0xc000
	v_lshlrev_b32_e32 v1, 3, v1
	v_lshl_add_u64 v[6:7], s[12:13], 0, v[4:5]
	s_mov_b32 m0, s30
	v_ashrrev_i32_e32 v153, 31, v152
	v_and_or_b32 v2, v1, 56, v3
	global_load_lds_dwordx4 v[6:7], off
	v_lshlrev_b64 v[6:7], 1, v[152:153]
	s_add_i32 s31, s29, 0xc400
	v_ashrrev_i32_e32 v1, 31, v0
	v_lshl_add_u64 v[8:9], s[12:13], 0, v[6:7]
	s_mov_b32 m0, s31
	v_lshlrev_b64 v[48:49], 1, v[0:1]
	global_load_lds_dwordx4 v[8:9], off
	v_lshl_add_u64 v[0:1], s[10:11], 0, v[48:49]
	s_mov_b32 m0, s29
	v_ashrrev_i32_e32 v3, 31, v2
	s_or_b32 s10, s6, 64
	global_load_lds_dwordx4 v[0:1], off
	v_lshl_add_u64 v[0:1], v[0:1], 0, s[22:23]
	s_add_i32 m0, s29, 0x400
	v_lshlrev_b64 v[50:51], 1, v[2:3]
	s_lshl_b32 s38, s36, 10
	s_ashr_i32 s11, s10, 31
	s_or_b32 s7, s1, 0x400
	global_load_lds_dwordx4 v[0:1], off
	v_lshl_add_u64 v[0:1], s[34:35], 0, v[50:51]
	s_add_i32 s34, s25, s38
	s_lshl_b64 s[12:13], s[10:11], 11
	s_add_u32 s36, s18, s12
	s_addc_u32 s37, s19, s13
	s_add_u32 s12, s20, s12
	s_addc_u32 s13, s21, s13
	s_lshl_b64 s[10:11], s[10:11], 7
	s_add_u32 s10, s52, s10
	s_mov_b32 m0, s34
	s_addc_u32 s11, s53, s11
	s_add_i32 s35, s26, s1
	global_load_lds_dwordx4 v[0:1], off
	v_lshl_add_u64 v[0:1], s[36:37], 0, v[4:5]
	s_mov_b32 m0, s35
	s_waitcnt vmcnt(0)
	s_waitcnt vmcnt(0) lgkmcnt(0)
	s_barrier
	global_load_lds_dwordx4 v[0:1], off
	v_lshl_add_u64 v[0:1], s[36:37], 0, v[6:7]
	s_add_i32 s36, s26, s7
	s_mov_b32 m0, s36
	s_add_i32 s37, s38, 0
	global_load_lds_dwordx4 v[0:1], off
	v_lshl_add_u64 v[0:1], s[12:13], 0, v[48:49]
	s_add_i32 m0, s29, 0x4000
	v_lshlrev_b32_e32 v62, 8, v148
	global_load_lds_dwordx4 v[0:1], off
	v_lshl_add_u64 v[0:1], v[0:1], 0, s[22:23]
	s_add_i32 m0, s29, 0x4400
	v_and_b32_e32 v63, 0x70, v10
	global_load_lds_dwordx4 v[0:1], off
	v_lshl_add_u64 v[0:1], s[10:11], 0, v[50:51]
	s_add_i32 m0, s37, 0x16000
	v_bitop3_b32 v180, v144, v62, v63 bitop3:0xde
	global_load_lds_dwordx4 v[0:1], off
	v_add_u32_e32 v181, 0, v180
	ds_read_b128 v[16:19], v181 offset:49152
	ds_read_b128 v[20:23], v181 offset:57344
	s_waitcnt lgkmcnt(0)
	v_mfma_f32_32x32x16_bf16 v[32:47], v[16:19], v[140:143], 0
	v_or_b32_e32 v64, 32, v144
	v_bitop3_b32 v182, v64, v62, v63 bitop3:0xde
	v_add_u32_e32 v183, 0, v182
	ds_read_b128 v[54:57], v183 offset:49152
	ds_read_b128 v[58:61], v183 offset:57344
	v_or_b32_e32 v65, 64, v144
	v_bitop3_b32 v184, v65, v62, v63 bitop3:0xde
	v_add_u32_e32 v185, 0, v184
	v_mfma_f32_32x32x16_bf16 v[16:31], v[20:23], v[140:143], 0
	v_or_b32_e32 v66, 0x60, v144
	v_bitop3_b32 v186, v66, v62, v63 bitop3:0xde
	v_add_u32_e32 v187, 0, v186
	v_and_b32_e32 v53, 0x70, v53
	v_mov_b64_e32 v[0:1], s[68:69]
	v_mov_b64_e32 v[14:15], s[82:83]
	v_mov_b64_e32 v[2:3], s[70:71]
	s_waitcnt lgkmcnt(0)
	v_mfma_f32_32x32x16_bf16 v[32:47], v[54:57], v[136:139], v[32:47]
	v_mov_b64_e32 v[4:5], s[72:73]
	v_mov_b64_e32 v[6:7], s[74:75]
	v_mov_b64_e32 v[8:9], s[76:77]
	v_mov_b64_e32 v[10:11], s[78:79]
	v_mov_b64_e32 v[12:13], s[80:81]
	v_lshl_add_u64 v[154:155], s[52:53], 0, v[50:51]
	v_lshl_add_u64 v[156:157], s[20:21], 0, v[48:49]
	v_mfma_f32_32x32x16_bf16 v[16:31], v[58:61], v[136:139], v[16:31]
	ds_read_b128 v[54:57], v185 offset:49152
	ds_read_b128 v[58:61], v185 offset:57344
	v_lshl_add_u32 v177, v148, 2, s28
	s_mov_b32 s46, -1
	s_movk_i32 s48, 0x4000
	s_mov_b32 s47, 0x8000
	v_mov_b32_e32 v178, 0
	s_waitcnt lgkmcnt(0)
	v_mfma_f32_32x32x16_bf16 v[32:47], v[54:57], v[132:135], v[32:47]
	v_mfma_f32_32x32x16_bf16 v[16:31], v[58:61], v[132:135], v[16:31]
	ds_read_b128 v[54:57], v187 offset:49152
	ds_read_b128 v[58:61], v187 offset:57344
	s_waitcnt lgkmcnt(0)
	v_mfma_f32_32x32x16_bf16 v[32:47], v[54:57], v[128:131], v[32:47]
	v_or_b32_e32 v54, 0x80, v144
	v_bitop3_b32 v188, v54, v62, v63 bitop3:0xde
	v_add_u32_e32 v189, 0, v188
	v_mfma_f32_32x32x16_bf16 v[16:31], v[58:61], v[128:131], v[16:31]
	ds_read_b128 v[54:57], v189 offset:49152
	ds_read_b128 v[58:61], v189 offset:57344
	s_waitcnt lgkmcnt(0)
	v_mfma_f32_32x32x16_bf16 v[32:47], v[54:57], v[124:127], v[32:47]
	v_or_b32_e32 v54, 0xa0, v144
	v_bitop3_b32 v190, v54, v62, v63 bitop3:0xde
	v_add_u32_e32 v191, 0, v190
	v_mfma_f32_32x32x16_bf16 v[16:31], v[58:61], v[124:127], v[16:31]
	ds_read_b128 v[54:57], v191 offset:49152
	ds_read_b128 v[58:61], v191 offset:57344
	s_waitcnt lgkmcnt(0)
	v_mfma_f32_32x32x16_bf16 v[32:47], v[54:57], v[120:123], v[32:47]
	v_or_b32_e32 v54, 0xc0, v144
	v_bitop3_b32 v192, v54, v62, v63 bitop3:0xde
	v_add_u32_e32 v193, 0, v192
	v_mfma_f32_32x32x16_bf16 v[16:31], v[58:61], v[120:123], v[16:31]
	ds_read_b128 v[54:57], v193 offset:49152
	ds_read_b128 v[58:61], v193 offset:57344
	s_waitcnt lgkmcnt(0)
	v_mfma_f32_32x32x16_bf16 v[32:47], v[54:57], v[116:119], v[32:47]
	v_or_b32_e32 v54, 0xe0, v144
	v_bitop3_b32 v194, v54, v62, v63 bitop3:0xde
	v_add_u32_e32 v195, 0, v194
	v_lshlrev_b32_e32 v62, 7, v148
	v_bitop3_b32 v196, v144, v62, v53 bitop3:0xde
	v_add_u32_e32 v197, s25, v196
	v_bitop3_b32 v198, v64, v62, v53 bitop3:0xde
	v_mfma_f32_32x32x16_bf16 v[16:31], v[58:61], v[116:119], v[16:31]
	ds_read_b128 v[54:57], v195 offset:49152
	ds_read_b128 v[58:61], v195 offset:57344
	v_add_u32_e32 v199, s25, v198
	v_bitop3_b32 v200, v65, v62, v53 bitop3:0xde
	v_add_u32_e32 v201, s25, v200
	v_bitop3_b32 v202, v66, v62, v53 bitop3:0xde
	v_add_u32_e32 v203, s25, v202
	s_waitcnt lgkmcnt(0)
	v_mfma_f32_32x32x16_bf16 v[32:47], v[54:57], v[112:115], v[32:47]
	v_mfma_f32_32x32x16_bf16 v[16:31], v[58:61], v[112:115], v[16:31]
	ds_read_b128 v[54:57], v197
	ds_read_b128 v[58:61], v197 offset:4096
	s_waitcnt lgkmcnt(0)
	v_mfma_f32_32x32x16_bf16 v[32:47], v[54:57], v[108:111], v[32:47]
	v_mfma_f32_32x32x16_bf16 v[16:31], v[58:61], v[108:111], v[16:31]
	ds_read_b128 v[54:57], v199
	ds_read_b128 v[58:61], v199 offset:4096
	s_waitcnt lgkmcnt(0)
	v_mfma_f32_32x32x16_bf16 v[32:47], v[54:57], v[104:107], v[32:47]
	v_mfma_f32_32x32x16_bf16 v[16:31], v[58:61], v[104:107], v[16:31]
	ds_read_b128 v[54:57], v201
	ds_read_b128 v[58:61], v201 offset:4096
	s_waitcnt lgkmcnt(0)
	v_mfma_f32_32x32x16_bf16 v[32:47], v[54:57], v[100:103], v[32:47]
	v_mfma_f32_32x32x16_bf16 v[16:31], v[58:61], v[100:103], v[16:31]
	ds_read_b128 v[54:57], v203
	ds_read_b128 v[58:61], v203 offset:4096
	s_waitcnt lgkmcnt(0)
	v_mfma_f32_32x32x16_bf16 v[32:47], v[54:57], v[96:99], v[32:47]
	v_mfma_f32_32x32x16_bf16 v[16:31], v[58:61], v[96:99], v[16:31]
	s_nop 10
	v_max_f32_e32 v53, v33, v33
	v_max_f32_e32 v54, v32, v32
	v_max_f32_e32 v53, v54, v53
	v_max3_f32 v53, v53, v34, v35
	v_max3_f32 v53, v53, v36, v37
	v_max3_f32 v53, v53, v38, v39
	v_max3_f32 v53, v53, v40, v41
	v_max3_f32 v53, v53, v42, v43
	v_max3_f32 v53, v53, v44, v45
	v_max3_f32 v53, v53, v46, v47
	v_max3_f32 v53, v53, v16, v17
	v_max3_f32 v53, v53, v18, v19
	v_max3_f32 v53, v53, v20, v21
	v_max3_f32 v53, v53, v22, v23
	v_max3_f32 v53, v53, v24, v25
	v_max3_f32 v53, v53, v26, v27
	v_max3_f32 v53, v53, v28, v29
	v_max3_f32 v53, v53, v30, v31
	v_mov_b32_e32 v54, v53
	s_nop 1
	v_permlane32_swap_b32_e32 v53, v54
	v_max_f32_e32 v54, v54, v54
	v_max_f32_e32 v53, v53, v53
	v_max_f32_e32 v53, v53, v54
	v_add_f32_e32 v54, 0x7149f2ca, v53
	v_max_f32_e32 v53, 0xf149f2ca, v53
	v_cmp_ge_f32_e32 vcc, s27, v54
	v_sub_f32_e32 v54, 0xf149f2ca, v53
	v_mul_f32_e32 v54, 0x3dd53b94, v54
	v_exp_f32_e32 v54, v54
	s_cmp_eq_u64 vcc, exec
	s_cselect_b64 vcc, -1, 0
	v_cndmask_b32_e32 v217, v53, v174, vcc
	v_cndmask_b32_e64 v204, v54, 1.0, vcc
	v_mul_f32_e32 v54, 0xbdd53b94, v217
	v_mov_b32_e32 v53, v54
	v_fmamk_f32 v32, v32, 0x3dd53b94, v54
	v_fmamk_f32 v33, v33, 0x3dd53b94, v54
	v_fmamk_f32 v34, v34, 0x3dd53b94, v54
	v_fmamk_f32 v35, v35, 0x3dd53b94, v54
	v_fmamk_f32 v36, v36, 0x3dd53b94, v54
	v_fmamk_f32 v37, v37, 0x3dd53b94, v54
	v_fmamk_f32 v38, v38, 0x3dd53b94, v54
	v_fmamk_f32 v39, v39, 0x3dd53b94, v54
	v_fmamk_f32 v40, v40, 0x3dd53b94, v54
	v_fmamk_f32 v41, v41, 0x3dd53b94, v54
	v_fmamk_f32 v42, v42, 0x3dd53b94, v54
	v_fmamk_f32 v43, v43, 0x3dd53b94, v54
	v_fmamk_f32 v44, v44, 0x3dd53b94, v54
	v_fmamk_f32 v45, v45, 0x3dd53b94, v54
	v_fmamk_f32 v46, v46, 0x3dd53b94, v54
	v_fmac_f32_e32 v53, 0x3dd53b94, v47
	v_exp_f32_e32 v228, v32
	v_exp_f32_e32 v230, v33
	v_exp_f32_e32 v231, v34
	v_exp_f32_e32 v232, v35
	v_exp_f32_e32 v233, v36
	v_exp_f32_e32 v234, v37
	v_exp_f32_e32 v227, v38
	v_exp_f32_e32 v229, v39
	v_exp_f32_e32 v222, v40
	v_exp_f32_e32 v224, v41
	v_exp_f32_e32 v225, v42
	v_exp_f32_e32 v226, v43
	v_exp_f32_e32 v219, v44
	v_exp_f32_e32 v220, v45
	v_exp_f32_e32 v221, v46
	v_exp_f32_e32 v223, v53
	v_pk_fma_f32 v[168:169], v[30:31], s[24:25], v[54:55] op_sel_hi:[1,0,0]
	v_pk_fma_f32 v[158:159], v[28:29], s[24:25], v[54:55] op_sel_hi:[1,0,0]
	v_pk_fma_f32 v[160:161], v[26:27], s[24:25], v[54:55] op_sel_hi:[1,0,0]
	v_pk_fma_f32 v[162:163], v[24:25], s[24:25], v[54:55] op_sel_hi:[1,0,0]
	v_pk_fma_f32 v[164:165], v[22:23], s[24:25], v[54:55] op_sel_hi:[1,0,0]
	v_pk_fma_f32 v[166:167], v[20:21], s[24:25], v[54:55] op_sel_hi:[1,0,0]
	v_pk_fma_f32 v[170:171], v[18:19], s[24:25], v[54:55] op_sel_hi:[1,0,0]
	v_pk_fma_f32 v[172:173], v[16:17], s[24:25], v[54:55] op_sel_hi:[1,0,0]
	s_lshl_b32 s7, s0, 8
	v_cmp_gt_u32_e64 s[0:1], 32, v52
	v_mov_b64_e32 v[62:63], v[14:15]
	v_mov_b64_e32 v[46:47], v[14:15]
	v_mov_b64_e32 v[30:31], v[14:15]
	s_or_b32 s40, s6, 0x80
	s_add_i32 s41, s7, 0x18c0
	v_mov_b64_e32 v[60:61], v[12:13]
	v_mov_b64_e32 v[58:59], v[10:11]
	v_mov_b64_e32 v[56:57], v[8:9]
	v_mov_b64_e32 v[54:55], v[6:7]
	v_mov_b64_e32 v[52:53], v[4:5]
	v_mov_b64_e32 v[50:51], v[2:3]
	v_mov_b64_e32 v[48:49], v[0:1]
	v_mov_b64_e32 v[44:45], v[12:13]
	v_mov_b64_e32 v[42:43], v[10:11]
	v_mov_b64_e32 v[40:41], v[8:9]
	v_mov_b64_e32 v[38:39], v[6:7]
	v_mov_b64_e32 v[36:37], v[4:5]
	v_mov_b64_e32 v[34:35], v[2:3]
	v_mov_b64_e32 v[32:33], v[0:1]
	v_mov_b64_e32 v[28:29], v[12:13]
	v_mov_b64_e32 v[26:27], v[10:11]
	v_mov_b64_e32 v[24:25], v[8:9]
	v_mov_b64_e32 v[22:23], v[6:7]
	v_mov_b64_e32 v[20:21], v[4:5]
	v_mov_b64_e32 v[18:19], v[2:3]
	v_mov_b64_e32 v[16:17], v[0:1]
	s_mov_b32 s6, 0
